# grid barrier: XCD leader posts the per-XCC release before its own acquire invalidate instead of after it
# speedup vs baseline: 1.0145x; 1.0093x over previous
.LBB0_1523:
	s_or_b64 exec, exec, s[10:11]
	s_mov_b64 s[10:11], exec
	v_mbcnt_lo_u32_b32 v0, s10, 0
	v_mbcnt_hi_u32_b32 v0, s11, v0
	v_cmp_eq_u32_e32 vcc, 0, v0
	s_and_saveexec_b64 s[12:13], vcc
	s_cbranch_execz .LBB0_1525
	s_bcnt1_i32_b64 s2, s[10:11]
	v_mov_b32_e32 v0, s2
	v_mov_b32_e32 v1, 0x2000
	global_atomic_add v1, v0, s[8:9] offset:1024
.LBB0_1525:
	s_or_b64 exec, exec, s[12:13]
	s_waitcnt vmcnt(0)
	buffer_inv sc1
	s_waitcnt vmcnt(0)
